# v30 + prep phase: XOR swizzle of the 16-byte k-groups in the weight transposition tile (ds_write_b16 bank conflicts 8-way -> 2-way; reader ds_read_b128 uses the same swizzle)
# speedup vs baseline: 1.0003x; 1.0003x over previous
.LBB0_17:
	s_or_b64 exec, exec, s[6:7]
	s_load_dwordx16 s[36:51], s[0:1], 0x40
	v_mov_b32_e32 v72, v213
	s_cmpk_gt_i32 s2, 0x29f
	s_waitcnt lgkmcnt(0)
	v_writelane_b32 v252, s36, 10
	s_nop 1
	v_writelane_b32 v252, s37, 11
	v_writelane_b32 v252, s38, 12
	v_writelane_b32 v252, s39, 13
	v_writelane_b32 v252, s40, 14
	v_writelane_b32 v252, s41, 15
	v_writelane_b32 v252, s42, 16
	v_writelane_b32 v252, s43, 17
	v_writelane_b32 v252, s44, 18
	v_writelane_b32 v252, s45, 19
	v_writelane_b32 v252, s46, 20
	v_writelane_b32 v252, s47, 21
	v_writelane_b32 v252, s48, 22
	v_writelane_b32 v252, s49, 23
	v_writelane_b32 v252, s50, 24
	v_writelane_b32 v252, s51, 25
	s_cbranch_scc1 .LBB0_138
	v_ashrrev_i32_e32 v2, 3, v72
	s_movk_i32 s0, 0x210
	v_writelane_b32 v252, s4, 26
	v_mul_lo_u32 v5, v2, s0
	s_movk_i32 s0, 0x80
	v_writelane_b32 v252, s5, 27
	v_cmp_gt_i32_e64 s[6:7], s0, v72
	s_add_u32 s0, s24, 0x4c00000
	v_writelane_b32 v252, s0, 28
	s_addc_u32 s0, s25, 0
	s_add_u32 s88, s24, 0x2000000
	s_addc_u32 s89, s25, 0
	s_add_u32 s90, s24, 0x6218000
	s_addc_u32 s91, s25, 0
	s_add_u32 s92, s24, 0x622e000
	s_addc_u32 s93, s25, 0
	s_add_u32 s94, s24, 0x1c00000
	s_addc_u32 s95, s25, 0
	s_add_u32 s3, s24, 0x1400000
	s_addc_u32 s33, s25, 0
	s_mov_b32 s5, s52
	s_add_u32 s52, s24, 0x6210000
	s_addc_u32 s4, s25, 0
	s_add_u32 s54, s24, 0x6214000
	s_addc_u32 s55, s25, 0
	s_add_u32 s56, s24, 0x1000000
	s_addc_u32 s57, s25, 0
	s_add_u32 s58, s82, 0x1000
	s_addc_u32 s59, s83, 0
	v_writelane_b32 v252, s0, 30
	s_add_u32 s60, s84, 0x1000
	s_addc_u32 s61, s85, 0
	v_writelane_b32 v252, s72, 32
	v_ashrrev_i32_e32 v74, 4, v72
	v_ashrrev_i32_e32 v75, 31, v74
	v_writelane_b32 v252, s73, 33
	v_writelane_b32 v252, s74, 34
	v_writelane_b32 v252, s75, 35
	v_writelane_b32 v252, s76, 36
	v_writelane_b32 v252, s77, 37
	v_writelane_b32 v252, s78, 38
	v_writelane_b32 v252, s79, 39
	v_lshlrev_b32_e32 v0, 2, v72
	v_lshlrev_b64 v[92:93], 2, v[74:75]
	s_mov_b64 s[10:11], 0x780
	v_writelane_b32 v252, s80, 40
	v_and_b32_e32 v0, 60, v0
	v_lshl_add_u64 v[100:101], v[92:93], 0, s[10:11]
	s_mov_b64 s[10:11], 0x400
	v_writelane_b32 v252, s81, 41
	v_lshlrev_b32_e32 v6, 8, v74
	v_lshlrev_b32_e32 v7, 2, v0
	v_lshl_add_u64 v[102:103], v[92:93], 0, s[10:11]
	s_mov_b64 s[10:11], 0x700
	v_writelane_b32 v252, s82, 42
	v_add3_u32 v91, 0, v6, v7
	v_lshlrev_b32_e32 v7, 4, v72
	v_lshl_add_u64 v[104:105], v[92:93], 0, s[10:11]
	s_mov_b64 s[10:11], 0x480
	v_writelane_b32 v252, s83, 43
	v_and_b32_e32 v8, 0x70, v7
	s_add_u32 s62, s24, 0x6200000
	v_lshl_add_u64 v[106:107], v[92:93], 0, s[10:11]
	s_mov_b64 s[10:11], 0x680
	v_writelane_b32 v252, s84, 44
	v_lshlrev_b32_e32 v3, 2, v2
	v_lshrrev_b32_e32 v4, 1, v2
	v_and_b32_e32 v117, 63, v72
	v_lshrrev_b32_e32 v198, 5, v72
	v_xor_b32_e32 v198, v198, v72
	v_and_b32_e32 v198, 7, v198
	v_lshlrev_b32_e32 v198, 4, v198
	v_add_u32_e32 v119, v5, v198
	v_lshlrev_b32_e32 v8, 7, v72
	s_addc_u32 s63, s25, 0
	v_lshl_add_u64 v[108:109], v[92:93], 0, s[10:11]
	s_mov_b64 s[10:11], 0x500
	v_writelane_b32 v252, s85, 45
	v_mov_b32_e32 v77, 0
	v_lshl_add_u32 v1, v74, 1, 0
	v_and_b32_e32 v3, 16, v3
	v_and_b32_e32 v4, 12, v4
	v_and_b32_e32 v2, 35, v2
	v_lshl_add_u32 v6, v117, 2, 0
	v_add_u32_e32 v78, 32, v74
	v_add_u32_e32 v80, 64, v74
	v_add_u32_e32 v82, 0x60, v74
	v_add_u32_e32 v84, 0x80, v74
	v_add_u32_e32 v86, 0xa0, v74
	v_add_u32_e32 v88, 0xc0, v74
	v_add_u32_e32 v90, 0xe0, v74
	v_mul_u32_u24_e32 v5, 0x210, v0
	v_and_b32_e32 v8, 0xffffe000, v8
	s_add_u32 s64, s24, 0x6208000
	v_and_b32_e32 v9, 7, v72
	v_mov_b32_e32 v10, 0x100
	v_and_b32_e32 v96, 0xf0, v7
	v_lshl_add_u64 v[110:111], v[92:93], 0, s[10:11]
	s_mov_b64 s[10:11], 0x600
	s_mov_b64 s[12:13], 0x580
	v_writelane_b32 v252, s86, 46
	s_mov_b32 s1, 0
	v_cmp_gt_u32_e64 s[8:9], 64, v72
	v_ashrrev_i32_e32 v73, 31, v78
	v_ashrrev_i32_e32 v79, 31, v80
	v_ashrrev_i32_e32 v81, 31, v82
	v_ashrrev_i32_e32 v83, 31, v84
	v_ashrrev_i32_e32 v85, 31, v86
	v_ashrrev_i32_e32 v87, 31, v88
	v_ashrrev_i32_e32 v89, 31, v90
	s_addc_u32 s65, s25, 0
	v_lshl_or_b32 v94, v9, 4, v10
	v_mov_b32_e32 v95, v77
	v_or3_b32 v121, v2, v3, v4
	v_mov_b32_e32 v97, v77
	v_or_b32_e32 v98, 8, v96
	v_mov_b32_e32 v99, v77
	v_lshlrev_b32_e32 v76, 2, v0
	v_and_b32_e32 v198, 3, v72
	v_lshlrev_b32_e32 v198, 4, v198
	v_xor_b32_e32 v198, v198, v1
	v_add_u32_e32 v198, v198, v5
	v_bfe_u32 v199, v72, 2, 1
	v_lshlrev_b32_e32 v199, 6, v199
	v_add_u32_e32 v123, v198, v199
	v_xor_b32_e32 v199, 64, v199
	v_add_u32_e32 v198, v198, v199
	v_add_u32_e32 v125, v6, v8
	s_movk_i32 s66, 0x7fff
	s_mov_b32 s67, s2
	s_mov_b32 s100, s2
	v_mov_b32_e32 v127, 1
	v_lshl_add_u64 v[112:113], v[92:93], 0, s[10:11]
	v_lshl_add_u64 v[114:115], v[92:93], 0, s[12:13]
	v_writelane_b32 v252, s87, 47
	s_branch .LBB0_21

.LBB0_93:
	s_waitcnt vmcnt(7)
	v_pk_mul_f32 v[40:41], v[0:1], v[116:117] op_sel_hi:[1,0]
	v_pk_mul_f32 v[42:43], v[2:3], v[116:117] op_sel_hi:[1,0]
	v_and_b32_sdwa v70, v41, v127 dst_sel:DWORD dst_unused:UNUSED_PAD src0_sel:WORD_1 src1_sel:DWORD
	v_and_b32_sdwa v71, v40, v127 dst_sel:DWORD dst_unused:UNUSED_PAD src0_sel:WORD_1 src1_sel:DWORD
	s_waitcnt vmcnt(6)
	v_pk_mul_f32 v[44:45], v[4:5], v[118:119] op_sel_hi:[1,0]
	v_and_b32_sdwa v129, v43, v127 dst_sel:DWORD dst_unused:UNUSED_PAD src0_sel:WORD_1 src1_sel:DWORD
	s_waitcnt vmcnt(5)
	v_pk_mul_f32 v[48:49], v[8:9], v[122:123] op_sel_hi:[1,0]
	v_add3_u32 v171, v41, v70, s66
	v_add3_u32 v172, v40, v71, s66
	v_and_b32_sdwa v40, v45, v127 dst_sel:DWORD dst_unused:UNUSED_PAD src0_sel:WORD_1 src1_sel:DWORD
	v_and_b32_sdwa v41, v44, v127 dst_sel:DWORD dst_unused:UNUSED_PAD src0_sel:WORD_1 src1_sel:DWORD
	v_and_b32_sdwa v131, v42, v127 dst_sel:DWORD dst_unused:UNUSED_PAD src0_sel:WORD_1 src1_sel:DWORD
	v_pk_mul_f32 v[46:47], v[6:7], v[118:119] op_sel_hi:[1,0]
	s_waitcnt vmcnt(4)
	v_pk_mul_f32 v[52:53], v[12:13], v[128:129] op_sel_hi:[1,0]
	v_add3_u32 v175, v45, v40, s66
	v_add3_u32 v176, v44, v41, s66
	v_and_b32_sdwa v40, v49, v127 dst_sel:DWORD dst_unused:UNUSED_PAD src0_sel:WORD_1 src1_sel:DWORD
	v_and_b32_sdwa v41, v48, v127 dst_sel:DWORD dst_unused:UNUSED_PAD src0_sel:WORD_1 src1_sel:DWORD
	v_pk_mul_f32 v[50:51], v[10:11], v[122:123] op_sel_hi:[1,0]
	s_waitcnt vmcnt(3)
	v_pk_mul_f32 v[56:57], v[16:17], v[134:135] op_sel_hi:[1,0]
	v_pk_mul_f32 v[58:59], v[18:19], v[134:135] op_sel_hi:[1,0]
	v_add3_u32 v179, v49, v40, s66
	v_add3_u32 v180, v48, v41, s66
	v_and_b32_sdwa v40, v53, v127 dst_sel:DWORD dst_unused:UNUSED_PAD src0_sel:WORD_1 src1_sel:DWORD
	v_and_b32_sdwa v41, v52, v127 dst_sel:DWORD dst_unused:UNUSED_PAD src0_sel:WORD_1 src1_sel:DWORD
	v_add3_u32 v133, v43, v129, s66
	v_add3_u32 v135, v42, v131, s66
	v_and_b32_sdwa v42, v47, v127 dst_sel:DWORD dst_unused:UNUSED_PAD src0_sel:WORD_1 src1_sel:DWORD
	v_and_b32_sdwa v43, v46, v127 dst_sel:DWORD dst_unused:UNUSED_PAD src0_sel:WORD_1 src1_sel:DWORD
	v_pk_mul_f32 v[54:55], v[14:15], v[128:129] op_sel_hi:[1,0]
	s_waitcnt vmcnt(2)
	v_pk_mul_f32 v[60:61], v[24:25], v[144:145] op_sel_hi:[1,0]
	v_add3_u32 v183, v53, v40, s66
	v_add3_u32 v184, v52, v41, s66
	v_and_b32_sdwa v40, v57, v127 dst_sel:DWORD dst_unused:UNUSED_PAD src0_sel:WORD_1 src1_sel:DWORD
	v_and_b32_sdwa v41, v56, v127 dst_sel:DWORD dst_unused:UNUSED_PAD src0_sel:WORD_1 src1_sel:DWORD
	v_add3_u32 v137, v47, v42, s66
	v_add3_u32 v139, v46, v43, s66
	v_and_b32_sdwa v42, v51, v127 dst_sel:DWORD dst_unused:UNUSED_PAD src0_sel:WORD_1 src1_sel:DWORD
	v_and_b32_sdwa v43, v50, v127 dst_sel:DWORD dst_unused:UNUSED_PAD src0_sel:WORD_1 src1_sel:DWORD
	v_pk_mul_f32 v[62:63], v[26:27], v[144:145] op_sel_hi:[1,0]
	s_waitcnt vmcnt(1)
	v_pk_mul_f32 v[64:65], v[28:29], v[158:159] op_sel_hi:[1,0]
	v_add3_u32 v185, v57, v40, s66
	v_add3_u32 v186, v56, v41, s66
	v_and_b32_sdwa v40, v61, v127 dst_sel:DWORD dst_unused:UNUSED_PAD src0_sel:WORD_1 src1_sel:DWORD
	v_and_b32_sdwa v41, v60, v127 dst_sel:DWORD dst_unused:UNUSED_PAD src0_sel:WORD_1 src1_sel:DWORD
	v_add3_u32 v141, v51, v42, s66
	v_add3_u32 v145, v50, v43, s66
	v_and_b32_sdwa v42, v55, v127 dst_sel:DWORD dst_unused:UNUSED_PAD src0_sel:WORD_1 src1_sel:DWORD
	v_and_b32_sdwa v43, v54, v127 dst_sel:DWORD dst_unused:UNUSED_PAD src0_sel:WORD_1 src1_sel:DWORD
	v_pk_mul_f32 v[66:67], v[30:31], v[158:159] op_sel_hi:[1,0]
	s_waitcnt vmcnt(0)
	v_pk_mul_f32 v[68:69], v[32:33], v[164:165] op_sel_hi:[1,0]
	v_add3_u32 v187, v61, v40, s66
	v_add3_u32 v188, v60, v41, s66
	v_and_b32_sdwa v40, v65, v127 dst_sel:DWORD dst_unused:UNUSED_PAD src0_sel:WORD_1 src1_sel:DWORD
	v_and_b32_sdwa v41, v64, v127 dst_sel:DWORD dst_unused:UNUSED_PAD src0_sel:WORD_1 src1_sel:DWORD
	v_add3_u32 v159, v55, v42, s66
	v_add3_u32 v168, v54, v43, s66
	v_and_b32_sdwa v42, v59, v127 dst_sel:DWORD dst_unused:UNUSED_PAD src0_sel:WORD_1 src1_sel:DWORD
	v_and_b32_sdwa v43, v58, v127 dst_sel:DWORD dst_unused:UNUSED_PAD src0_sel:WORD_1 src1_sel:DWORD
	v_add3_u32 v189, v65, v40, s66
	v_add3_u32 v190, v64, v41, s66
	v_and_b32_sdwa v40, v69, v127 dst_sel:DWORD dst_unused:UNUSED_PAD src0_sel:WORD_1 src1_sel:DWORD
	v_and_b32_sdwa v41, v68, v127 dst_sel:DWORD dst_unused:UNUSED_PAD src0_sel:WORD_1 src1_sel:DWORD
	v_add3_u32 v169, v59, v42, s66
	v_add3_u32 v170, v58, v43, s66
	v_and_b32_sdwa v42, v63, v127 dst_sel:DWORD dst_unused:UNUSED_PAD src0_sel:WORD_1 src1_sel:DWORD
	v_and_b32_sdwa v43, v62, v127 dst_sel:DWORD dst_unused:UNUSED_PAD src0_sel:WORD_1 src1_sel:DWORD
	v_add3_u32 v191, v69, v40, s66
	v_add3_u32 v192, v68, v41, s66
	v_pk_mul_f32 v[40:41], v[34:35], v[164:165] op_sel_hi:[1,0]
	v_add3_u32 v173, v63, v42, s66
	v_add3_u32 v174, v62, v43, s66
	v_and_b32_sdwa v42, v67, v127 dst_sel:DWORD dst_unused:UNUSED_PAD src0_sel:WORD_1 src1_sel:DWORD
	v_and_b32_sdwa v43, v66, v127 dst_sel:DWORD dst_unused:UNUSED_PAD src0_sel:WORD_1 src1_sel:DWORD
	s_addk_i32 s36, 0x100
	v_add3_u32 v177, v67, v42, s66
	v_add3_u32 v178, v66, v43, s66
	v_and_b32_sdwa v42, v41, v127 dst_sel:DWORD dst_unused:UNUSED_PAD src0_sel:WORD_1 src1_sel:DWORD
	v_and_b32_sdwa v43, v40, v127 dst_sel:DWORD dst_unused:UNUSED_PAD src0_sel:WORD_1 src1_sel:DWORD
	s_cmp_ge_u32 s36, s68
	v_add3_u32 v181, v41, v42, s66
	v_add3_u32 v182, v40, v43, s66
	s_cselect_b64 s[34:35], -1, 0
	s_cmp_lt_u32 s36, s68
	v_mov_b64_e32 v[58:59], v[18:19]
	v_mov_b64_e32 v[56:57], v[16:17]
	v_mov_b64_e32 v[42:43], v[2:3]
	v_mov_b64_e32 v[46:47], v[6:7]
	v_mov_b64_e32 v[50:51], v[10:11]
	v_mov_b64_e32 v[54:55], v[14:15]
	v_mov_b64_e32 v[40:41], v[0:1]
	v_mov_b64_e32 v[44:45], v[4:5]
	v_mov_b64_e32 v[48:49], v[8:9]
	v_mov_b64_e32 v[52:53], v[12:13]
	v_mov_b64_e32 v[70:71], v[34:35]
	v_mov_b64_e32 v[68:69], v[32:33]
	v_mov_b64_e32 v[66:67], v[30:31]
	v_mov_b64_e32 v[64:65], v[28:29]
	v_mov_b64_e32 v[62:63], v[26:27]
	v_mov_b64_e32 v[60:61], v[24:25]
	v_mov_b32_e32 v129, v120
	v_mov_b32_e32 v131, v124
	v_mov_b32_e32 v193, v126
	v_mov_b32_e32 v194, v130
	v_mov_b32_e32 v195, v132
	v_mov_b32_e32 v196, v136
	v_mov_b32_e32 v197, v138
	v_mov_b32_e32 v165, v140
	ds_write_b16_d16_hi v123, v172
	ds_write_b16_d16_hi v123, v171 offset:528
	ds_write_b16_d16_hi v198, v176
	ds_write_b16_d16_hi v198, v175 offset:528
	ds_write_b16_d16_hi v123, v180 offset:128
	ds_write_b16_d16_hi v123, v179 offset:656
	ds_write_b16_d16_hi v198, v184 offset:128
	ds_write_b16_d16_hi v198, v183 offset:656
	ds_write_b16_d16_hi v123, v186 offset:256
	ds_write_b16_d16_hi v123, v185 offset:784
	ds_write_b16_d16_hi v198, v188 offset:256
	ds_write_b16_d16_hi v198, v187 offset:784
	ds_write_b16_d16_hi v123, v190 offset:384
	ds_write_b16_d16_hi v123, v189 offset:912
	ds_write_b16_d16_hi v198, v192 offset:384
	ds_write_b16_d16_hi v198, v191 offset:912
	ds_write_b16_d16_hi v123, v135 offset:1056
	ds_write_b16_d16_hi v123, v133 offset:1584
	ds_write_b16_d16_hi v198, v139 offset:1056
	ds_write_b16_d16_hi v198, v137 offset:1584
	ds_write_b16_d16_hi v123, v145 offset:1184
	ds_write_b16_d16_hi v123, v141 offset:1712
	ds_write_b16_d16_hi v198, v168 offset:1184
	ds_write_b16_d16_hi v198, v159 offset:1712
	ds_write_b16_d16_hi v123, v170 offset:1312
	ds_write_b16_d16_hi v123, v169 offset:1840
	ds_write_b16_d16_hi v198, v174 offset:1312
	ds_write_b16_d16_hi v198, v173 offset:1840
	ds_write_b16_d16_hi v123, v178 offset:1440
	ds_write_b16_d16_hi v123, v177 offset:1968
	ds_write_b16_d16_hi v198, v182 offset:1440
	ds_write_b16_d16_hi v198, v181 offset:1968
	s_cbranch_scc0 .LBB0_92
	v_lshl_add_u64 v[40:41], v[148:149], 0, s[28:29]
	global_load_dwordx4 v[40:43], v[40:41], off nt
	s_and_b64 vcc, exec, s[10:11]
	v_lshl_add_u64 v[164:165], s[20:21], 0, v[92:93]
	s_cbranch_vccnz .LBB0_109
	global_load_dword v116, v[164:165], off offset:1024
	s_and_b64 vcc, exec, s[12:13]
	v_lshl_add_u64 v[166:167], s[22:23], 0, v[92:93]
	s_cbranch_vccnz .LBB0_110
